# norm_phase row loop software-pipelined (next row O/gate loads prefetched into v202-233, counted vmcnt(4))
# baseline (speedup 1.0000x reference)
; __device__ __forceinline__ int TID() { int t = threadIdx.x; asm volatile("" : "+v"(t)); return t; }
; __device__ __forceinline__ int BID() { int t = blockIdx.x; asm volatile("" : "+s"(t)); return t; }
; __device__ __forceinline__ void norm_phase(ArgsP a_, int kind) { const ArgsP a = a_;
;     const int lane = TID() & 63, wv = TID() >> 6; const int gw = BID() * 8 + wv, nw = gridDim.x * 8;
;     const bf16_t* OB = (const bf16_t*)(a->ws + B_PART); bf16_t* ON = (bf16_t*)(a->ws + B_ACT); const unsigned char* proj = a->ws + B_PROJ;
;     const float* ngp = (kind == 1 ? AIN(17) : AIN(25)) + lane * 32;
;     f32x4 gq[8];
; #pragma unroll
;     for (int q = 0; q < 8; ++q) gq[q] = *(const f32x4*)(ngp + 4 * q);
;     const bf16_t* Gg = (const bf16_t*)(proj + (size_t)MP * 8192);
;     for (int row = gw; row < M_; row += nw) {
;         const size_t o = (size_t)row * 2048 + lane * 32;
;         u32x4 xr[4], gr[4];
; #pragma unroll
;         for (int q = 0; q < 4; ++q) xr[q] = *(const u32x4*)(OB + o + 8 * q);
;         if (kind == 1) {
; #pragma unroll
;             for (int q = 0; q < 4; ++q) gr[q] = *(const u32x4*)(Gg + o + 8 * q);
.LBB0_184:
	s_and_b64 vcc, exec, s[18:19]
	s_cbranch_vccz .LBB0_100
	v_readlane_b32 s4, v254, 61
	s_cmp_gt_i32 s4, 2
	s_mov_b64 s[4:5], -1
	s_cbranch_scc0 .LBB0_766
	v_readlane_b32 s4, v254, 61
	s_cmp_lt_i32 s4, 4
	s_mov_b64 s[4:5], -1
	s_cbranch_scc1 .LBB0_445
	v_readlane_b32 s4, v254, 61
	s_cmp_gt_i32 s4, 4
	s_mov_b64 s[4:5], -1
	s_cbranch_scc0 .LBB0_219
	v_mov_b32_e32 v36, v186
	v_mov_b32_e32 v0, v186
	s_mov_b32 s4, s93
	s_lshl_b32 s24, s4, 3
	v_readlane_b32 s4, v255, 0
	s_cmp_eq_u32 s4, 1
	v_ashrrev_i32_e32 v34, 6, v0
	s_cselect_b64 s[18:19], -1, 0
	s_cmp_lg_u32 s4, 1
	v_add_u32_e32 v16, s24, v34
	s_movk_i32 s13, 0x4480
	s_cselect_b64 s[4:5], -1, 0
	v_cmp_gt_i32_e32 vcc, s13, v16
	s_and_saveexec_b64 s[22:23], vcc
	s_cbranch_execz .LBB0_209
	s_and_b64 s[26:27], s[18:19], exec
	s_movk_i32 s13, 0x88
	s_cselect_b32 s13, s13, 0xc8
	s_add_u32 s26, s0, s13
	s_addc_u32 s27, s1, 0
	s_load_dwordx2 s[26:27], s[26:27], 0x0
	v_lshlrev_b32_e32 v0, 7, v36
	v_and_b32_e32 v30, 0x1f80, v0
	v_ashrrev_i32_e32 v35, 31, v34
	s_waitcnt lgkmcnt(0)
	global_load_dwordx4 v[0:3], v30, s[26:27] offset:80
	global_load_dwordx4 v[4:7], v30, s[26:27] offset:64
	global_load_dwordx4 v[8:11], v30, s[26:27] offset:112
	global_load_dwordx4 v[12:15], v30, s[26:27] offset:96
	global_load_dwordx4 v[18:21], v30, s[26:27] offset:16
	global_load_dwordx4 v[22:25], v30, s[26:27]
	global_load_dwordx4 v[26:29], v30, s[26:27] offset:48
	s_nop 0
	global_load_dwordx4 v[30:33], v30, s[26:27] offset:32
	s_ashr_i32 s25, s24, 31
	v_lshl_add_u64 v[34:35], v[34:35], 0, s[24:25]
	v_lshlrev_b64 v[34:35], 12, v[34:35]
	v_and_b32_e32 v36, 63, v36
	v_lshl_or_b32 v34, v36, 6, v34
	v_lshl_add_u64 v[34:35], s[2:3], 0, v[34:35]
	s_mov_b64 s[24:25], 0x292e0030
	v_lshl_add_u64 v[66:67], v[34:35], 0, s[24:25]
	s_mov_b64 s[24:25], 0
	s_mov_b32 s26, 0xeebfffd0
	s_mov_b32 s27, -1
	s_nop 0
	v_lshl_add_u64 v[234:235], v[66:67], 0, s[26:27]
	global_load_dwordx4 v[202:205], v[234:235], off
	global_load_dwordx4 v[206:209], v[234:235], off offset:16
	global_load_dwordx4 v[210:213], v[234:235], off offset:32
	global_load_dwordx4 v[214:217], v[234:235], off offset:48
	s_andn2_b64 vcc, exec, s[18:19]
	s_cbranch_vccnz .Lnorm_pre_nog
	global_load_dwordx4 v[218:221], v[66:67], off offset:-48
	global_load_dwordx4 v[222:225], v[66:67], off offset:-32
	global_load_dwordx4 v[226:229], v[66:67], off offset:-16
	global_load_dwordx4 v[230:233], v[66:67], off
.Lnorm_pre_nog:
	s_waitcnt vmcnt(0)
	s_branch .Lnorm_body

; __device__ __forceinline__ void norm_phase(ArgsP a_, int kind) { const ArgsP a = a_;
;     ...
;     for (int row = gw; row < M_; row += nw) {
;         const size_t o = (size_t)row * 2048 + lane * 32;
;         u32x4 xr[4], gr[4];
; #pragma unroll
;         for (int q = 0; q < 4; ++q) xr[q] = *(const u32x4*)(OB + o + 8 * q);
;         if (kind == 1) {
; #pragma unroll
;             for (int q = 0; q < 4; ++q) gr[q] = *(const u32x4*)(Gg + o + 8 * q);
;         }
;         float x[32];
; #pragma unroll
;         for (int q = 0; q < 4; ++q)
; #pragma unroll
;             for (int e = 0; e < 4; ++e) { x[8 * q + 2 * e] = __uint_as_float(xr[q][e] << 16); x[8 * q + 2 * e + 1] = __uint_as_float(xr[q][e] & 0xffff0000u); }
;         float mean = 0.f, rstd;
;         if (kind == 1) {
;             float s1 = 0.f;
; #pragma unroll
;             for (int e = 0; e < 32; ++e) s1 += x[e];
;             s1 += __shfl_xor(s1, 1); s1 += __shfl_xor(s1, 2); s1 += __shfl_xor(s1, 4); s1 += __shfl_xor(s1, 8);
;             mean = s1 * (1.f / 512.f);
;             float s2 = 0.f;
; #pragma unroll
;             for (int e = 0; e < 32; ++e) { const float d = x[e] - mean; s2 += d * d; }
;             s2 += __shfl_xor(s2, 1); s2 += __shfl_xor(s2, 2); s2 += __shfl_xor(s2, 4); s2 += __shfl_xor(s2, 8);
;             rstd = rsqrtf(s2 * (1.f / 512.f) + LN_EPS);
;         } else {
;             float s2 = 0.f;
; #pragma unroll
;             for (int e = 0; e < 32; ++e) s2 += x[e] * x[e];
;             s2 += __shfl_xor(s2, 1); s2 += __shfl_xor(s2, 2); s2 += __shfl_xor(s2, 4);
;             rstd = rsqrtf(s2 * (1.f / 256.f) + LN_EPS);
.LBB0_191:
	s_waitcnt vmcnt(4)
.Lnorm_body:
	v_readlane_b32 s26, v254, 47
	v_readlane_b32 s27, v254, 48
	v_mov_b32_e32 v62, v202
	v_mov_b32_e32 v63, v203
	v_mov_b32_e32 v64, v204
	v_mov_b32_e32 v65, v205
	v_mov_b32_e32 v58, v206
	v_mov_b32_e32 v59, v207
	v_mov_b32_e32 v60, v208
	v_mov_b32_e32 v61, v209
	v_mov_b32_e32 v54, v210
	v_mov_b32_e32 v55, v211
	v_mov_b32_e32 v56, v212
	v_mov_b32_e32 v57, v213
	v_mov_b32_e32 v50, v214
	v_mov_b32_e32 v51, v215
	v_mov_b32_e32 v52, v216
	v_mov_b32_e32 v53, v217
	v_mov_b32_e32 v34, v218
	v_mov_b32_e32 v35, v219
	v_mov_b32_e32 v36, v220
	v_mov_b32_e32 v37, v221
	v_mov_b32_e32 v38, v222
	v_mov_b32_e32 v39, v223
	v_mov_b32_e32 v40, v224
	v_mov_b32_e32 v41, v225
	v_mov_b32_e32 v42, v226
	v_mov_b32_e32 v43, v227
	v_mov_b32_e32 v44, v228
	v_mov_b32_e32 v45, v229
	v_mov_b32_e32 v46, v230
	v_mov_b32_e32 v47, v231
	v_mov_b32_e32 v48, v232
	v_mov_b32_e32 v49, v233
	v_cndmask_b32_e64 v68, 0, 1, s[18:19]
	v_cmp_ne_u32_e64 s[40:41], 1, v68
	v_add_u32_e32 v238, s60, v16
	v_cmp_ge_i32_e32 vcc, s92, v238
	s_cbranch_vccz .LBB0_193
	v_lshl_add_u64 v[236:237], v[66:67], 0, s[26:27]
	s_mov_b32 s26, 0xeebfffd0
	s_mov_b32 s27, -1
	s_nop 0
	v_lshl_add_u64 v[234:235], v[236:237], 0, s[26:27]
	global_load_dwordx4 v[202:205], v[234:235], off
	global_load_dwordx4 v[206:209], v[234:235], off offset:16
	global_load_dwordx4 v[210:213], v[234:235], off offset:32
	global_load_dwordx4 v[214:217], v[234:235], off offset:48
	s_andn2_b64 vcc, exec, s[18:19]
	s_cbranch_vccnz .LBB0_193
	global_load_dwordx4 v[218:221], v[236:237], off offset:-48
	global_load_dwordx4 v[222:225], v[236:237], off offset:-32
	global_load_dwordx4 v[226:229], v[236:237], off offset:-16
	global_load_dwordx4 v[230:233], v[236:237], off
.LBB0_193:
	v_lshlrev_b32_e32 v84, 16, v62
	v_and_b32_e32 v85, 0xffff0000, v62
	v_lshlrev_b32_e32 v82, 16, v63
	v_and_b32_e32 v83, 0xffff0000, v63
	v_lshlrev_b32_e32 v78, 16, v64
	v_and_b32_e32 v79, 0xffff0000, v64
	v_lshlrev_b32_e32 v80, 16, v65
	v_and_b32_e32 v81, 0xffff0000, v65
	v_lshlrev_b32_e32 v70, 16, v58
	v_and_b32_e32 v71, 0xffff0000, v58
	v_lshlrev_b32_e32 v72, 16, v59
	v_and_b32_e32 v73, 0xffff0000, v59
	v_lshlrev_b32_e32 v74, 16, v60
	v_and_b32_e32 v75, 0xffff0000, v60
	v_lshlrev_b32_e32 v76, 16, v61
	v_and_b32_e32 v77, 0xffff0000, v61
	v_lshlrev_b32_e32 v58, 16, v54
	v_and_b32_e32 v59, 0xffff0000, v54
	v_lshlrev_b32_e32 v60, 16, v55
	v_and_b32_e32 v61, 0xffff0000, v55
	v_lshlrev_b32_e32 v62, 16, v56
	v_and_b32_e32 v63, 0xffff0000, v56
	v_lshlrev_b32_e32 v64, 16, v57
	v_and_b32_e32 v65, 0xffff0000, v57
	v_lshlrev_b32_e32 v54, 16, v50
	v_and_b32_e32 v55, 0xffff0000, v50
	v_lshlrev_b32_e32 v50, 16, v51
	v_and_b32_e32 v51, 0xffff0000, v51
	v_lshlrev_b32_e32 v56, 16, v52
	v_and_b32_e32 v57, 0xffff0000, v52
	v_lshlrev_b32_e32 v52, 16, v53
	v_and_b32_e32 v53, 0xffff0000, v53
	s_andn2_b64 vcc, exec, s[4:5]
	s_mov_b64 s[26:27], -1
	s_cbranch_vccnz .LBB0_195
	v_pk_mul_f32 v[68:69], v[84:85], v[84:85]
	v_pk_mul_f32 v[86:87], v[82:83], v[82:83]
	v_add_f32_e32 v68, v68, v69
	v_add_f32_e32 v68, v86, v68
	v_pk_mul_f32 v[88:89], v[78:79], v[78:79]
	v_add_f32_e32 v68, v87, v68
	v_add_f32_e32 v68, v88, v68
	v_pk_mul_f32 v[90:91], v[80:81], v[80:81]
	v_add_f32_e32 v68, v89, v68
	v_add_f32_e32 v68, v90, v68
	v_pk_mul_f32 v[92:93], v[70:71], v[70:71]
	v_add_f32_e32 v68, v91, v68
	v_add_f32_e32 v68, v92, v68
	v_pk_mul_f32 v[94:95], v[72:73], v[72:73]
	v_add_f32_e32 v68, v93, v68
	v_add_f32_e32 v68, v94, v68
	v_pk_mul_f32 v[96:97], v[74:75], v[74:75]
	v_add_f32_e32 v68, v95, v68
	v_add_f32_e32 v68, v96, v68
	v_pk_mul_f32 v[98:99], v[76:77], v[76:77]
	v_add_f32_e32 v68, v97, v68
	v_add_f32_e32 v68, v98, v68
	v_pk_mul_f32 v[100:101], v[58:59], v[58:59]
	v_add_f32_e32 v68, v99, v68
	v_add_f32_e32 v68, v100, v68
	v_pk_mul_f32 v[102:103], v[60:61], v[60:61]
	v_add_f32_e32 v68, v101, v68
	v_add_f32_e32 v68, v102, v68
	v_pk_mul_f32 v[104:105], v[62:63], v[62:63]
	v_add_f32_e32 v68, v103, v68
	v_add_f32_e32 v68, v104, v68
	v_pk_mul_f32 v[106:107], v[64:65], v[64:65]
	v_add_f32_e32 v68, v105, v68
	v_add_f32_e32 v68, v106, v68
	v_pk_mul_f32 v[108:109], v[54:55], v[54:55]
	v_add_f32_e32 v68, v107, v68
	v_add_f32_e32 v68, v108, v68
	v_pk_mul_f32 v[110:111], v[50:51], v[50:51]
	v_add_f32_e32 v68, v109, v68
	v_add_f32_e32 v68, v110, v68
	v_pk_mul_f32 v[112:113], v[56:57], v[56:57]
	v_add_f32_e32 v68, v111, v68
	v_and_b32_e32 v86, 64, v188
	v_add_f32_e32 v68, v112, v68
	v_xor_b32_e32 v69, 1, v188
	v_add_u32_e32 v86, 64, v86
	v_pk_mul_f32 v[114:115], v[52:53], v[52:53]
	v_add_f32_e32 v68, v113, v68
	v_cmp_lt_i32_e32 vcc, v69, v86
	v_add_f32_e32 v68, v114, v68
	v_add_f32_e32 v68, v115, v68
	v_cndmask_b32_e32 v69, v188, v69, vcc
	v_lshlrev_b32_e32 v69, 2, v69
	ds_bpermute_b32 v69, v69, v68
	s_mov_b64 s[26:27], 0
	s_waitcnt lgkmcnt(0)
	v_add_f32_e32 v68, v68, v69
	v_xor_b32_e32 v69, 2, v188
	v_cmp_lt_i32_e32 vcc, v69, v86
	s_nop 1
	v_cndmask_b32_e32 v69, v188, v69, vcc
	v_lshlrev_b32_e32 v69, 2, v69
	ds_bpermute_b32 v69, v69, v68
	s_waitcnt lgkmcnt(0)
	v_add_f32_e32 v69, v68, v69
	v_xor_b32_e32 v68, 4, v188
	v_cmp_lt_i32_e32 vcc, v68, v86
	s_nop 1
	v_cndmask_b32_e32 v68, v188, v68, vcc
	v_lshlrev_b32_e32 v68, 2, v68
	ds_bpermute_b32 v86, v68, v69
